# split128 + LDS-DMA sample loop + prompt attention: Q waited before the next-item prefetch is issued, no vmcnt drain inside the key-tile loop (prefetch now overlaps compute)
# speedup vs baseline: 1.0100x; 1.0100x over previous
; #define LAS __attribute__((address_space(3)))
; __device__ __forceinline__ void attn_mfma_phase(LAS unsigned char* lds, const bf16* QKVb, bf16* OPART, float2* ML, int tid, int wave, int lane) {
;     ...
;     for (int item = blockIdx.x; item < 1536; item += gridDim.x) {
;         int h, b, r, bk; decode(item, h, b, r, bk);
;         const int d = 1 << (2 * b), L0 = bk * 256;
; #pragma unroll
;         for (int c = 0; c < 6; ++c) { const int e = tid + NTHR * c, j = e >> 3, ch = e & 7;
;             *(LAS v4u*)(kimg + j * RSK + 16 * ch) = pk[c]; *(LAS v4u*)(vimg + j * RSV + 16 * ch) = pv[c]; }
;         const int l0 = L0 + 32 * wave;
;         const int tok_q = (l0 + i) * d + r;
;         const bf16* qp = QKVb + (size_t)tok_q * INW + C_QA + h * 64 + 8 * hh;
;         bf16x8 qf[4];
; #pragma unroll
;         for (int ks = 0; ks < 4; ++ks) qf[ks] = *(const bf16x8*)(qp + 16 * ks);
;         __syncthreads();
;         if (item + (int)gridDim.x < 1536) issue(item + gridDim.x);
.LBB0_1018:
	s_lshl_b32 s87, s84, 8
	s_add_i32 s87, s87, s2
	s_lshl_b32 s70, s1, 1
	v_or_b32_e32 v2, s87, v133
	v_lshlrev_b32_e32 v2, s70, v2
	v_readlane_b32 s70, v254, 55
	v_readlane_b32 s71, v254, 56
	v_add_u32_e32 v148, s33, v2
	s_lshl_b32 s94, s0, 6
	v_mov_b64_e32 v[2:3], s[70:71]
	v_mad_i64_i32 v[2:3], s[70:71], v148, s3, v[2:3]
	s_ashr_i32 s95, s94, 31
	v_lshl_add_u64 v[2:3], s[94:95], 1, v[2:3]
	v_lshl_add_u64 v[2:3], v[2:3], 0, v[142:143]
	global_load_dwordx4 v[114:117], v[2:3], off
	global_load_dwordx4 v[118:121], v[2:3], off offset:32
	global_load_dwordx4 v[122:125], v[2:3], off offset:64
	global_load_dwordx4 v[126:129], v[2:3], off offset:96
	s_movk_i32 s33, 128
	s_add_i32 s86, s86, s33
	s_cmpk_gt_i32 s86, 0x5ff
	s_cselect_b64 s[72:73], -1, 0
	v_add_u32_e32 v2, v135, v155
	s_and_b64 vcc, exec, s[72:73]
	s_waitcnt vmcnt(5)
	ds_write_b128 v159, v[70:73]
	s_waitcnt vmcnt(4)
	ds_write_b128 v2, v[66:69] offset:55296
	ds_write_b128 v160, v[78:81]
	ds_write_b128 v161, v[74:77] offset:55296
	ds_write_b128 v159, v[86:89] offset:18432
	ds_write_b128 v168, v[82:85] offset:55296
	ds_write_b128 v169, v[94:97]
	ds_write_b128 v170, v[90:93] offset:55296
	ds_write_b128 v159, v[102:105] offset:36864
	ds_write_b128 v171, v[98:101] offset:55296
	ds_write_b128 v172, v[110:113]
	ds_write_b128 v173, v[106:109] offset:55296
	s_waitcnt lgkmcnt(0)
	s_barrier
	s_waitcnt vmcnt(0)
	s_cbranch_vccnz .LBB0_1039
	s_mul_hi_i32 s33, s86, 0x2aaaaaab
	s_lshr_b32 s70, s33, 31
	s_ashr_i32 s96, s33, 5
	s_add_i32 s96, s96, s70
	s_mul_i32 s33, s96, 0xc0
	s_sub_i32 s70, s86, s33
	s_cmp_lt_i32 s70, 64
	s_mov_b32 s84, 0
	s_cbranch_scc1 .LBB0_1025
	s_cmpk_gt_u32 s70, 0x7f
	s_mov_b64 s[92:93], -1
	s_cbranch_scc0 .LBB0_1022
	s_add_i32 s33, s70, 0xffffff80
	s_lshr_b32 s84, s33, 2
	s_and_b32 s33, s70, 3
	s_mov_b64 s[92:93], 0

; #define LAS __attribute__((address_space(3)))
; #define MFMA32(a, b, c) __builtin_amdgcn_mfma_f32_32x32x16_bf16((a), (b), (c), 0, 0, 0)
; __device__ __forceinline__ int crow(int reg, int hh) { return (reg & 3) + 8 * (reg >> 2) + 4 * hh; }
; __device__ __forceinline__ void attn_mfma_phase(LAS unsigned char* lds, const bf16* QKVb, bf16* OPART, float2* ML, int tid, int wave, int lane) {
;     ...
;         for (int kt = kt0; kt < 5; ++kt) {
;             const int jb = 32 * wave + 32 * kt;
;             const LAS unsigned char* kp = kimg + (jb + i) * RSK + 16 * hh;
;             f32x16 s;
; #pragma unroll
;             for (int e = 0; e < 16; ++e) s[e] = 0.f;
; #pragma unroll
;             for (int ks = 0; ks < 4; ++ks) { const bf16x8 kf = *(const LAS bf16x8*)(kp + 32 * ks); s = MFMA32(kf, qf[ks], s); }
;             float tm = -1e30f;
;             if (kt == 0) {
; #pragma unroll
;                 for (int e = 0; e < 16; ++e) s[e] = crow(e, hh) < i ? -1e30f : s[e];
;             } else if (kt == 4) {
; #pragma unroll
;                 for (int e = 0; e < 16; ++e) s[e] = crow(e, hh) > i ? -1e30f : s[e];
;             }
.LBB0_1041:
	v_add_u32_e32 v38, 0, v175
	ds_read_b128 v[34:37], v38
	s_cmp_gt_i32 s87, 3
	s_mov_b64 s[92:93], -1
	s_waitcnt lgkmcnt(0)
	v_mfma_f32_32x32x16_bf16 v[50:65], v[34:37], v[114:117], 0
	ds_read_b128 v[34:37], v38 offset:32
	s_waitcnt lgkmcnt(0)
	v_mfma_f32_32x32x16_bf16 v[50:65], v[34:37], v[118:121], v[50:65]
	ds_read_b128 v[34:37], v38 offset:64
	s_waitcnt lgkmcnt(0)
	v_mfma_f32_32x32x16_bf16 v[50:65], v[34:37], v[122:125], v[50:65]
	ds_read_b128 v[34:37], v38 offset:96
	s_waitcnt lgkmcnt(0)
	v_mfma_f32_32x32x16_bf16 v[50:65], v[34:37], v[126:129], v[50:65]
	s_cbranch_scc0 .LBB0_1043
	s_nop 10
	v_cndmask_b32_e64 v34, v50, v174, s[6:7]
	v_cndmask_b32_e64 v35, v174, v51, s[8:9]
	v_cndmask_b32_e64 v36, v52, v174, s[10:11]
	v_cndmask_b32_e64 v37, v53, v174, s[12:13]
	v_cndmask_b32_e64 v38, v54, v174, s[14:15]
	v_cndmask_b32_e64 v39, v55, v174, s[16:17]
	v_cndmask_b32_e64 v40, v56, v174, s[18:19]
	v_cndmask_b32_e64 v41, v57, v174, s[20:21]
	v_cndmask_b32_e64 v42, v58, v174, s[22:23]
	v_cndmask_b32_e64 v43, v59, v174, s[24:25]
	v_cndmask_b32_e64 v44, v60, v174, s[26:27]
	v_cndmask_b32_e64 v45, v61, v174, s[28:29]
	v_cndmask_b32_e64 v46, v62, v174, s[30:31]
	v_cndmask_b32_e64 v47, v63, v174, s[34:35]
	v_cndmask_b32_e64 v48, v64, v174, s[36:37]
	v_cndmask_b32_e64 v49, v65, v174, s[38:39]
	s_mov_b64 s[92:93], 0
